# grid barrier: waiting workgroups poll the global generation word instead of their XCD's word (one hop less on the release path)
# speedup vs baseline: 1.0034x; 1.0034x over previous
.LBB0_146:
	s_or_b64 exec, exec, s[14:15]
	v_cvt_f32_u32_e32 v4, v2
	s_waitcnt vmcnt(0)
	v_readfirstlane_b32 s2, v3
	v_sub_u32_e32 v3, 0, v2
	v_rcp_iflag_f32_e32 v4, v4
	v_add_u32_e32 v5, s2, v1
	v_mul_f32_e32 v4, 0x4f7ffffe, v4
	v_cvt_u32_f32_e32 v4, v4
	v_mul_lo_u32 v1, v3, v4
	v_mul_hi_u32 v1, v4, v1
	v_add_u32_e32 v1, v4, v1
	v_mul_hi_u32 v1, v5, v1
	v_mul_lo_u32 v3, v1, v2
	v_sub_u32_e32 v3, v5, v3
	v_add_u32_e32 v4, 1, v1
	v_cmp_ge_u32_e32 vcc, v3, v2
	s_nop 1
	v_cndmask_b32_e32 v1, v1, v4, vcc
	v_sub_u32_e32 v4, v3, v2
	v_cndmask_b32_e32 v3, v3, v4, vcc
	v_add_u32_e32 v4, 1, v1
	v_cmp_ge_u32_e32 vcc, v3, v2
	v_add_u32_e32 v3, 1, v5
	s_nop 0
	v_cndmask_b32_e32 v1, v1, v4, vcc
	v_mul_lo_u32 v4, v2, v1
	v_add_u32_e32 v2, v4, v2
	v_cmp_ne_u32_e32 vcc, v3, v2
	s_and_saveexec_b64 s[2:3], vcc
	s_xor_b64 s[12:13], exec, s[2:3]
	s_cbranch_execz .LBB0_160
	s_waitcnt lgkmcnt(0)
	v_mov_b32_e32 v0, 0
	s_add_u32 s20, s6, 0x43500
	s_addc_u32 s21, s7, 0
	global_load_dword v0, v0, s[20:21] sc1
	s_waitcnt vmcnt(0)
	v_cmp_eq_u32_e32 vcc, v0, v1
	s_and_saveexec_b64 s[14:15], vcc
	s_cbranch_execz .LBB0_159
	s_add_u32 s18, s6, 0x40200
	s_addc_u32 s19, s7, 0
	s_mov_b32 s2, 1
	s_mov_b64 s[24:25], 0
	v_mov_b32_e32 v0, 0
	s_branch .LBB0_150

.LBB0_264:
	s_or_b64 exec, exec, s[12:13]
	v_cvt_f32_u32_e32 v4, v2
	s_waitcnt vmcnt(0)
	v_readfirstlane_b32 s3, v3
	v_sub_u32_e32 v3, 0, v2
	v_rcp_iflag_f32_e32 v4, v4
	v_add_u32_e32 v5, s3, v1
	v_mul_f32_e32 v4, 0x4f7ffffe, v4
	v_cvt_u32_f32_e32 v4, v4
	v_mul_lo_u32 v1, v3, v4
	v_mul_hi_u32 v1, v4, v1
	v_add_u32_e32 v1, v4, v1
	v_mul_hi_u32 v1, v5, v1
	v_mul_lo_u32 v3, v1, v2
	v_sub_u32_e32 v3, v5, v3
	v_add_u32_e32 v4, 1, v1
	v_cmp_ge_u32_e32 vcc, v3, v2
	s_nop 1
	v_cndmask_b32_e32 v1, v1, v4, vcc
	v_sub_u32_e32 v4, v3, v2
	v_cndmask_b32_e32 v3, v3, v4, vcc
	v_add_u32_e32 v4, 1, v1
	v_cmp_ge_u32_e32 vcc, v3, v2
	v_add_u32_e32 v3, 1, v5
	s_nop 0
	v_cndmask_b32_e32 v1, v1, v4, vcc
	v_mul_lo_u32 v4, v2, v1
	v_add_u32_e32 v2, v4, v2
	v_cmp_ne_u32_e32 vcc, v3, v2
	s_and_saveexec_b64 s[10:11], vcc
	s_xor_b64 s[10:11], exec, s[10:11]
	s_cbranch_execz .LBB0_278
	s_waitcnt lgkmcnt(0)
	v_mov_b32_e32 v0, 0
	s_add_u32 s18, s6, 0x43500
	s_addc_u32 s19, s7, 0
	global_load_dword v0, v0, s[18:19] sc1
	s_waitcnt vmcnt(0)
	v_cmp_eq_u32_e32 vcc, v0, v1
	s_and_saveexec_b64 s[12:13], vcc
	s_cbranch_execz .LBB0_277
	s_add_u32 s14, s6, 0x40200
	s_addc_u32 s15, s7, 0
	s_mov_b32 s3, 1
	s_mov_b64 s[20:21], 0
	v_mov_b32_e32 v0, 0
	s_branch .LBB0_268

.LBB0_414:
	s_or_b64 exec, exec, s[10:11]
	v_cvt_f32_u32_e32 v4, v2
	s_waitcnt vmcnt(0)
	v_readfirstlane_b32 s8, v3
	v_sub_u32_e32 v3, 0, v2
	v_rcp_iflag_f32_e32 v4, v4
	v_add_u32_e32 v5, s8, v1
	v_mul_f32_e32 v4, 0x4f7ffffe, v4
	v_cvt_u32_f32_e32 v4, v4
	v_mul_lo_u32 v1, v3, v4
	v_mul_hi_u32 v1, v4, v1
	v_add_u32_e32 v1, v4, v1
	v_mul_hi_u32 v1, v5, v1
	v_mul_lo_u32 v3, v1, v2
	v_sub_u32_e32 v3, v5, v3
	v_add_u32_e32 v4, 1, v1
	v_cmp_ge_u32_e32 vcc, v3, v2
	s_nop 1
	v_cndmask_b32_e32 v1, v1, v4, vcc
	v_sub_u32_e32 v4, v3, v2
	v_cndmask_b32_e32 v3, v3, v4, vcc
	v_add_u32_e32 v4, 1, v1
	v_cmp_ge_u32_e32 vcc, v3, v2
	v_add_u32_e32 v3, 1, v5
	s_nop 0
	v_cndmask_b32_e32 v1, v1, v4, vcc
	v_mul_lo_u32 v4, v2, v1
	v_add_u32_e32 v2, v4, v2
	v_cmp_ne_u32_e32 vcc, v3, v2
	s_and_saveexec_b64 s[8:9], vcc
	s_xor_b64 s[8:9], exec, s[8:9]
	s_cbranch_execz .LBB0_428
	s_waitcnt lgkmcnt(0)
	v_mov_b32_e32 v0, 0
	s_add_u32 s14, s4, 0x43500
	s_addc_u32 s15, s5, 0
	global_load_dword v0, v0, s[14:15] sc1
	s_waitcnt vmcnt(0)
	v_cmp_eq_u32_e32 vcc, v0, v1
	s_and_saveexec_b64 s[10:11], vcc
	s_cbranch_execz .LBB0_427
	s_add_u32 s12, s4, 0x40200
	s_addc_u32 s13, s5, 0
	s_mov_b32 s16, 1
	s_mov_b64 s[24:25], 0
	v_mov_b32_e32 v0, 0
	s_branch .LBB0_418

.LBB0_672:
	s_or_b64 exec, exec, s[12:13]
	v_cvt_f32_u32_e32 v4, v2
	s_waitcnt vmcnt(0)
	v_readfirstlane_b32 s10, v3
	v_sub_u32_e32 v3, 0, v2
	v_rcp_iflag_f32_e32 v4, v4
	v_add_u32_e32 v5, s10, v1
	v_mul_f32_e32 v4, 0x4f7ffffe, v4
	v_cvt_u32_f32_e32 v4, v4
	v_mul_lo_u32 v1, v3, v4
	v_mul_hi_u32 v1, v4, v1
	v_add_u32_e32 v1, v4, v1
	v_mul_hi_u32 v1, v5, v1
	v_mul_lo_u32 v3, v1, v2
	v_sub_u32_e32 v3, v5, v3
	v_add_u32_e32 v4, 1, v1
	v_cmp_ge_u32_e32 vcc, v3, v2
	s_nop 1
	v_cndmask_b32_e32 v1, v1, v4, vcc
	v_sub_u32_e32 v4, v3, v2
	v_cndmask_b32_e32 v3, v3, v4, vcc
	v_add_u32_e32 v4, 1, v1
	v_cmp_ge_u32_e32 vcc, v3, v2
	v_add_u32_e32 v3, 1, v5
	s_nop 0
	v_cndmask_b32_e32 v1, v1, v4, vcc
	v_mul_lo_u32 v4, v2, v1
	v_add_u32_e32 v2, v4, v2
	v_cmp_ne_u32_e32 vcc, v3, v2
	s_and_saveexec_b64 s[10:11], vcc
	s_xor_b64 s[10:11], exec, s[10:11]
	s_cbranch_execz .LBB0_686
	s_waitcnt lgkmcnt(0)
	v_mov_b32_e32 v0, 0
	s_add_u32 s24, s6, 0x43500
	s_addc_u32 s25, s7, 0
	global_load_dword v0, v0, s[24:25] sc1
	s_waitcnt vmcnt(0)
	v_cmp_eq_u32_e32 vcc, v0, v1
	s_and_saveexec_b64 s[12:13], vcc
	s_cbranch_execz .LBB0_685
	s_add_u32 s14, s6, 0x40200
	s_addc_u32 s15, s7, 0
	s_mov_b32 s16, 1
	s_mov_b64 s[26:27], 0
	v_mov_b32_e32 v0, 0
	s_branch .LBB0_676

.LBB0_743:
	s_or_b64 exec, exec, s[12:13]
	v_cvt_f32_u32_e32 v4, v2
	s_waitcnt vmcnt(0)
	v_readfirstlane_b32 s10, v3
	v_sub_u32_e32 v3, 0, v2
	v_rcp_iflag_f32_e32 v4, v4
	v_add_u32_e32 v5, s10, v1
	v_mul_f32_e32 v4, 0x4f7ffffe, v4
	v_cvt_u32_f32_e32 v4, v4
	v_mul_lo_u32 v1, v3, v4
	v_mul_hi_u32 v1, v4, v1
	v_add_u32_e32 v1, v4, v1
	v_mul_hi_u32 v1, v5, v1
	v_mul_lo_u32 v3, v1, v2
	v_sub_u32_e32 v3, v5, v3
	v_add_u32_e32 v4, 1, v1
	v_cmp_ge_u32_e32 vcc, v3, v2
	s_nop 1
	v_cndmask_b32_e32 v1, v1, v4, vcc
	v_sub_u32_e32 v4, v3, v2
	v_cndmask_b32_e32 v3, v3, v4, vcc
	v_add_u32_e32 v4, 1, v1
	v_cmp_ge_u32_e32 vcc, v3, v2
	v_add_u32_e32 v3, 1, v5
	s_nop 0
	v_cndmask_b32_e32 v1, v1, v4, vcc
	v_mul_lo_u32 v4, v2, v1
	v_add_u32_e32 v2, v4, v2
	v_cmp_ne_u32_e32 vcc, v3, v2
	s_and_saveexec_b64 s[10:11], vcc
	s_xor_b64 s[10:11], exec, s[10:11]
	s_cbranch_execz .LBB0_757
	s_waitcnt lgkmcnt(0)
	v_mov_b32_e32 v0, 0
	s_add_u32 s16, s6, 0x43500
	s_addc_u32 s17, s7, 0
	global_load_dword v0, v0, s[16:17] sc1
	s_waitcnt vmcnt(0)
	v_cmp_eq_u32_e32 vcc, v0, v1
	s_and_saveexec_b64 s[12:13], vcc
	s_cbranch_execz .LBB0_756
	s_add_u32 s14, s6, 0x40200
	s_addc_u32 s15, s7, 0
	s_mov_b32 s18, 1
	s_mov_b64 s[24:25], 0
	v_mov_b32_e32 v0, 0
	s_branch .LBB0_747
